# cand C + final RMSNorm loop software-pipelined (norm row hoisted, next row prefetched, stores back to back) + tt==63 tile tail: all 17 loads in flight
# speedup vs baseline: 1.0189x; 1.0022x over previous
.LBB0_879:
	s_cmp_lg_u32 s16, 63
	s_cbranch_scc1 .LBB0_682
	v_readlane_b32 s16, v255, 18
	v_readlane_b32 s17, v255, 19
	s_nop 1
	v_lshl_add_u64 v[4:5], s[16:17], 0, v[114:115]
	global_load_dword v36, v[4:5], off
	v_readlane_b32 s16, v255, 23
	v_readlane_b32 s17, v255, 24
	s_nop 1
	v_lshl_add_u64 v[4:5], s[16:17], 0, v[114:115]
	global_load_dword v37, v[4:5], off
	v_readlane_b32 s16, v255, 44
	v_readlane_b32 s17, v255, 45
	s_nop 1
	v_lshl_add_u64 v[4:5], s[16:17], 0, v[114:115]
	s_nop 0
	v_add_co_u32_e32 v4, vcc, 0xfffea000, v4
	s_nop 1
	v_addc_co_u32_e32 v5, vcc, -1, v5, vcc
	s_mov_b32 s17, 0
	global_load_dword v38, v[4:5], off
	s_mov_b32 s16, 0x5800
	v_lshl_add_u64 v[6:7], v[4:5], 0, s[16:17]
	global_load_dword v39, v[6:7], off
	s_mov_b32 s16, 0xb000
	v_lshl_add_u64 v[6:7], v[4:5], 0, s[16:17]
	global_load_dword v40, v[6:7], off
	s_mov_b32 s16, 0x10800
	v_lshl_add_u64 v[6:7], v[4:5], 0, s[16:17]
	global_load_dword v41, v[6:7], off
	s_mov_b32 s16, 0x16000
	v_lshl_add_u64 v[6:7], v[4:5], 0, s[16:17]
	global_load_dword v42, v[6:7], off
	s_mov_b32 s16, 0x1b800
	v_lshl_add_u64 v[6:7], v[4:5], 0, s[16:17]
	global_load_dword v43, v[6:7], off
	s_mov_b32 s16, 0x21000
	v_lshl_add_u64 v[6:7], v[4:5], 0, s[16:17]
	global_load_dword v44, v[6:7], off
	s_mov_b32 s16, 0x26800
	v_lshl_add_u64 v[6:7], v[4:5], 0, s[16:17]
	global_load_dword v45, v[6:7], off
	s_mov_b32 s16, 0x2c000
	v_lshl_add_u64 v[6:7], v[4:5], 0, s[16:17]
	global_load_dword v46, v[6:7], off
	s_mov_b32 s16, 0x31800
	v_lshl_add_u64 v[6:7], v[4:5], 0, s[16:17]
	global_load_dword v47, v[6:7], off
	s_mov_b32 s16, 0x37000
	v_lshl_add_u64 v[6:7], v[4:5], 0, s[16:17]
	global_load_dword v48, v[6:7], off
	s_mov_b32 s16, 0x3c800
	v_lshl_add_u64 v[6:7], v[4:5], 0, s[16:17]
	global_load_dword v49, v[6:7], off
	s_mov_b32 s16, 0x42000
	v_lshl_add_u64 v[6:7], v[4:5], 0, s[16:17]
	global_load_dword v50, v[6:7], off
	s_mov_b32 s16, 0x47800
	v_lshl_add_u64 v[6:7], v[4:5], 0, s[16:17]
	global_load_dword v51, v[6:7], off
	s_mov_b32 s16, 0x4d000
	v_lshl_add_u64 v[6:7], v[4:5], 0, s[16:17]
	global_load_dword v52, v[6:7], off
	v_readlane_b32 s16, v254, 8
	v_readlane_b32 s17, v254, 9
	s_nop 1
	v_lshl_add_u64 v[2:3], s[16:17], 0, v[34:35]
	s_waitcnt vmcnt(16)
	v_lshlrev_b32_e32 v6, 16, v36
	v_and_b32_e32 v7, 0xffff0000, v36
	global_store_dwordx2 v[2:3], v[6:7], off
	s_mov_b64 s[16:17], 0x1000
	v_lshl_add_u64 v[10:11], v[2:3], 0, s[16:17]
	s_waitcnt vmcnt(16)
	v_lshlrev_b32_e32 v8, 16, v37
	v_and_b32_e32 v9, 0xffff0000, v37
	global_store_dwordx2 v[10:11], v[8:9], off
	v_readlane_b32 s16, v255, 40
	v_readlane_b32 s17, v255, 41
	s_nop 1
	v_lshl_add_u64 v[2:3], s[16:17], 0, v[34:35]
	s_mov_b32 s17, 0
	s_mov_b32 s16, 0x6280000
	v_lshl_add_u64 v[10:11], v[2:3], 0, s[16:17]
	s_waitcnt vmcnt(16)
	v_lshlrev_b32_e32 v6, 16, v38
	v_and_b32_e32 v7, 0xffff0000, v38
	global_store_dwordx2 v[10:11], v[6:7], off
	s_mov_b32 s16, 0x6281000
	v_lshl_add_u64 v[4:5], v[2:3], 0, s[16:17]
	s_waitcnt vmcnt(16)
	v_lshlrev_b32_e32 v8, 16, v39
	v_and_b32_e32 v9, 0xffff0000, v39
	global_store_dwordx2 v[4:5], v[8:9], off
	s_mov_b32 s16, 0x6282000
	v_lshl_add_u64 v[10:11], v[2:3], 0, s[16:17]
	s_waitcnt vmcnt(16)
	v_lshlrev_b32_e32 v6, 16, v40
	v_and_b32_e32 v7, 0xffff0000, v40
	global_store_dwordx2 v[10:11], v[6:7], off
	s_mov_b32 s16, 0x6283000
	v_lshl_add_u64 v[4:5], v[2:3], 0, s[16:17]
	s_waitcnt vmcnt(16)
	v_lshlrev_b32_e32 v8, 16, v41
	v_and_b32_e32 v9, 0xffff0000, v41
	global_store_dwordx2 v[4:5], v[8:9], off
	s_mov_b32 s16, 0x6284000
	v_lshl_add_u64 v[10:11], v[2:3], 0, s[16:17]
	s_waitcnt vmcnt(16)
	v_lshlrev_b32_e32 v6, 16, v42
	v_and_b32_e32 v7, 0xffff0000, v42
	global_store_dwordx2 v[10:11], v[6:7], off
	s_mov_b32 s16, 0x6285000
	v_lshl_add_u64 v[4:5], v[2:3], 0, s[16:17]
	s_waitcnt vmcnt(16)
	v_lshlrev_b32_e32 v8, 16, v43
	v_and_b32_e32 v9, 0xffff0000, v43
	global_store_dwordx2 v[4:5], v[8:9], off
	s_mov_b32 s16, 0x6286000
	v_lshl_add_u64 v[10:11], v[2:3], 0, s[16:17]
	s_waitcnt vmcnt(16)
	v_lshlrev_b32_e32 v6, 16, v44
	v_and_b32_e32 v7, 0xffff0000, v44
	global_store_dwordx2 v[10:11], v[6:7], off
	s_mov_b32 s16, 0x6287000
	v_lshl_add_u64 v[4:5], v[2:3], 0, s[16:17]
	s_waitcnt vmcnt(16)
	v_lshlrev_b32_e32 v8, 16, v45
	v_and_b32_e32 v9, 0xffff0000, v45
	global_store_dwordx2 v[4:5], v[8:9], off
	s_mov_b32 s16, 0x6288000
	v_lshl_add_u64 v[10:11], v[2:3], 0, s[16:17]
	s_waitcnt vmcnt(16)
	v_lshlrev_b32_e32 v6, 16, v46
	v_and_b32_e32 v7, 0xffff0000, v46
	global_store_dwordx2 v[10:11], v[6:7], off
	s_mov_b32 s16, 0x6289000
	v_lshl_add_u64 v[4:5], v[2:3], 0, s[16:17]
	s_waitcnt vmcnt(16)
	v_lshlrev_b32_e32 v8, 16, v47
	v_and_b32_e32 v9, 0xffff0000, v47
	global_store_dwordx2 v[4:5], v[8:9], off
	s_mov_b32 s16, 0x628a000
	v_lshl_add_u64 v[10:11], v[2:3], 0, s[16:17]
	s_waitcnt vmcnt(16)
	v_lshlrev_b32_e32 v6, 16, v48
	v_and_b32_e32 v7, 0xffff0000, v48
	global_store_dwordx2 v[10:11], v[6:7], off
	s_mov_b32 s16, 0x628b000
	v_lshl_add_u64 v[4:5], v[2:3], 0, s[16:17]
	s_waitcnt vmcnt(16)
	v_lshlrev_b32_e32 v8, 16, v49
	v_and_b32_e32 v9, 0xffff0000, v49
	global_store_dwordx2 v[4:5], v[8:9], off
	s_mov_b32 s16, 0x628c000
	v_lshl_add_u64 v[10:11], v[2:3], 0, s[16:17]
	s_waitcnt vmcnt(16)
	v_lshlrev_b32_e32 v6, 16, v50
	v_and_b32_e32 v7, 0xffff0000, v50
	global_store_dwordx2 v[10:11], v[6:7], off
	s_mov_b32 s16, 0x628d000
	v_lshl_add_u64 v[4:5], v[2:3], 0, s[16:17]
	s_waitcnt vmcnt(16)
	v_lshlrev_b32_e32 v8, 16, v51
	v_and_b32_e32 v9, 0xffff0000, v51
	global_store_dwordx2 v[4:5], v[8:9], off
	s_mov_b32 s16, 0x628e000
	v_lshl_add_u64 v[10:11], v[2:3], 0, s[16:17]
	s_waitcnt vmcnt(16)
	v_lshlrev_b32_e32 v6, 16, v52
	v_and_b32_e32 v7, 0xffff0000, v52
	global_store_dwordx2 v[10:11], v[6:7], off
	v_readlane_b32 s16, v253, 45
	v_readlane_b32 s17, v253, 46
	s_mov_b64 s[34:35], 0
	s_nop 0
	v_lshl_add_u64 v[2:3], s[16:17], 0, v[34:35]

.LBB0_1432:
	s_mov_b32 s0, 0
	s_mov_b64 s[6:7], 0
	s_mov_b32 s1, 0
	s_lshl_b32 s0, s82, 3
	s_add_i32 s0, s0, s85
	s_cmpk_gt_i32 s0, 0x407f
	s_waitcnt vmcnt(15)
	v_mbcnt_lo_u32_b32 v4, -1, 0
	v_mbcnt_hi_u32_b32 v4, -1, v4
	s_cbranch_scc1 .LBB0_1435
	v_and_b32_e32 v0, 64, v236
	v_add_u32_e32 v0, 64, v0
	v_xor_b32_e32 v1, 1, v236
	v_cmp_lt_i32_e32 vcc, v1, v0
	s_ashr_i32 s1, s0, 31
	s_lshl_b32 s2, s94, 3
	v_cndmask_b32_e32 v1, v236, v1, vcc
	s_waitcnt vmcnt(12)
	v_lshlrev_b32_e32 v6, 2, v1
	v_xor_b32_e32 v1, 2, v236
	v_cmp_lt_i32_e32 vcc, v1, v0
	s_lshl_b64 s[4:5], s[0:1], 12
	v_ashrrev_i32_e32 v5, 31, v4
	v_cndmask_b32_e32 v1, v236, v1, vcc
	v_lshlrev_b32_e32 v7, 2, v1
	v_xor_b32_e32 v1, 4, v236
	v_cmp_lt_i32_e32 vcc, v1, v0
	s_add_u32 s4, s90, s4
	v_lshlrev_b64 v[2:3], 4, v[4:5]
	v_cndmask_b32_e32 v1, v236, v1, vcc
	v_lshlrev_b32_e32 v8, 2, v1
	v_xor_b32_e32 v1, 8, v236
	v_cmp_lt_i32_e32 vcc, v1, v0
	s_addc_u32 s5, s91, s5
	s_ashr_i32 s3, s2, 31
	v_cndmask_b32_e32 v1, v236, v1, vcc
	v_lshlrev_b32_e32 v9, 2, v1
	v_xor_b32_e32 v1, 16, v236
	v_cmp_lt_i32_e32 vcc, v1, v0
	s_lshl_b64 s[8:9], s[0:1], 11
	v_mov_b32_e32 v12, 0x358637bd
	v_cndmask_b32_e32 v1, v236, v1, vcc
	v_lshlrev_b32_e32 v10, 2, v1
	v_xor_b32_e32 v1, 32, v236
	v_cmp_lt_i32_e32 vcc, v1, v0
	s_nop 1
	v_cndmask_b32_e32 v0, v236, v1, vcc
	v_lshlrev_b32_e32 v11, 2, v0
	v_lshl_add_u64 v[0:1], s[88:89], 0, v[2:3]
	v_lshl_add_u64 v[2:3], s[4:5], 0, v[2:3]
	s_mov_b64 s[4:5], 0x800
	v_lshl_add_u64 v[2:3], v[2:3], 0, s[4:5]
	s_lshl_b64 s[4:5], s[2:3], 12
	s_add_u32 s1, s6, s8
	s_addc_u32 s7, s7, s9
	s_add_u32 s6, s92, s1
	s_addc_u32 s7, s93, s7
	v_lshl_add_u64 v[4:5], v[4:5], 3, s[6:7]
	s_mov_b64 s[6:7], 0x5910400
	v_lshl_add_u64 v[4:5], v[4:5], 0, s[6:7]
	s_lshl_b64 s[6:7], s[2:3], 11
	s_mov_b32 s1, 0x800000
	global_load_dwordx4 v[50:53], v[0:1], off
	global_load_dwordx4 v[54:57], v[0:1], off offset:1024
	global_load_dwordx4 v[58:61], v[0:1], off offset:2048
	global_load_dwordx4 v[62:65], v[0:1], off offset:3072
	global_load_dwordx2 v[66:67], v[4:5], off offset:-1024
	global_load_dwordx2 v[68:69], v[4:5], off offset:-512
	global_load_dwordx2 v[70:71], v[4:5], off
	global_load_dwordx2 v[72:73], v[4:5], off offset:512
	v_lshl_add_u64 v[4:5], v[4:5], 0, s[6:7]
	s_waitcnt vmcnt(0)
	s_branch .Lfin_body
.Lfin_loop:
	s_waitcnt vmcnt(4)
.Lfin_body:
	v_mov_b32_e32 v18, v66
	v_mov_b32_e32 v19, v67
	v_mov_b32_e32 v20, v68
	v_mov_b32_e32 v21, v69
	v_mov_b32_e32 v22, v70
	v_mov_b32_e32 v23, v71
	v_mov_b32_e32 v24, v72
	v_mov_b32_e32 v25, v73
	s_add_i32 s0, s0, s2
	s_cmpk_gt_i32 s0, 0x407f
	s_cbranch_scc1 .Lfin_nopf
	global_load_dwordx2 v[66:67], v[4:5], off offset:-1024
	global_load_dwordx2 v[68:69], v[4:5], off offset:-512
	global_load_dwordx2 v[70:71], v[4:5], off
	global_load_dwordx2 v[72:73], v[4:5], off offset:512
	v_lshl_add_u64 v[4:5], v[4:5], 0, s[6:7]
.Lfin_nopf:
	v_lshlrev_b32_e32 v26, 16, v18
	v_and_b32_e32 v27, 0xffff0000, v18
	v_lshlrev_b32_e32 v18, 16, v19
	v_and_b32_e32 v19, 0xffff0000, v19
	v_lshlrev_b32_e32 v29, 16, v21
	v_lshlrev_b32_e32 v28, 16, v20
	v_and_b32_e32 v21, 0xffff0000, v21
	v_and_b32_e32 v20, 0xffff0000, v20
	v_and_b32_e32 v31, 0xffff0000, v22
	v_lshlrev_b32_e32 v33, 16, v24
	v_and_b32_e32 v35, 0xffff0000, v24
	v_mul_f32_e32 v32, v19, v19
	v_mul_f32_e32 v34, v27, v27
	v_lshlrev_b32_e32 v30, 16, v22
	v_lshlrev_b32_e32 v22, 16, v23
	v_and_b32_e32 v23, 0xffff0000, v23
	v_pk_mul_f32 v[36:37], v[20:21], v[20:21]
	v_mov_b32_e32 v39, v33
	v_mul_f32_e32 v38, v31, v31
	v_pk_fma_f32 v[42:43], v[18:19], v[18:19], v[32:33] op_sel_hi:[1,1,0]
	v_pk_fma_f32 v[44:45], v[26:27], v[26:27], v[34:35] op_sel_hi:[1,1,0]
	v_lshlrev_b32_e32 v24, 16, v25
	v_and_b32_e32 v25, 0xffff0000, v25
	v_mul_f32_e32 v40, v23, v23
	v_pk_fma_f32 v[36:37], v[28:29], v[28:29], v[36:37]
	v_pk_fma_f32 v[46:47], v[30:31], v[30:31], v[38:39] op_sel_hi:[1,1,0]
	v_mov_b32_e32 v32, v44
	v_mov_b32_e32 v38, v42
	v_mul_f32_e32 v13, v35, v35
	v_mul_f32_e32 v48, v24, v24
	v_mul_f32_e32 v49, v25, v25
	v_pk_fma_f32 v[40:41], v[22:23], v[22:23], v[40:41] op_sel_hi:[1,1,0]
	v_pk_add_f32 v[42:43], v[44:45], v[42:43]
	v_pk_add_f32 v[36:37], v[36:37], v[36:37] op_sel:[0,1] op_sel_hi:[1,0]
	v_pk_mul_f32 v[38:39], v[32:33], v[38:39]
	v_mov_b32_e32 v47, v48
	v_mov_b32_e32 v41, v49
	v_mov_b32_e32 v37, v13
	v_mov_b32_e32 v43, v39
	v_pk_add_f32 v[40:41], v[46:47], v[40:41]
	v_pk_add_f32 v[36:37], v[42:43], v[36:37]
	v_mov_b32_e32 v34, v33
	v_pk_add_f32 v[36:37], v[36:37], v[40:41]
	s_nop 0
	v_add_f32_e32 v13, v36, v37
	ds_bpermute_b32 v32, v6, v13
	s_waitcnt lgkmcnt(0)
	v_add_f32_e32 v13, v13, v32
	ds_bpermute_b32 v32, v7, v13
	s_waitcnt lgkmcnt(0)
	v_add_f32_e32 v13, v13, v32
	ds_bpermute_b32 v32, v8, v13
	s_waitcnt lgkmcnt(0)
	v_add_f32_e32 v13, v13, v32
	ds_bpermute_b32 v32, v9, v13
	s_waitcnt lgkmcnt(0)
	v_add_f32_e32 v13, v13, v32
	ds_bpermute_b32 v32, v10, v13
	s_waitcnt lgkmcnt(0)
	v_add_f32_e32 v13, v13, v32
	ds_bpermute_b32 v32, v11, v13
	s_waitcnt lgkmcnt(0)
	v_add_f32_e32 v13, v13, v32
	v_fmamk_f32 v13, v13, 0x3a800000, v12
	v_mul_f32_e32 v32, 0x4b800000, v13
	v_cmp_gt_f32_e32 vcc, s1, v13
	s_nop 1
	v_cndmask_b32_e32 v13, v13, v32, vcc
	v_rsq_f32_e32 v13, v13
	s_nop 0
	v_mul_f32_e32 v32, 0x45800000, v13
	v_cndmask_b32_e32 v32, v13, v32, vcc
	v_pk_mul_f32 v[26:27], v[32:33], v[26:27] op_sel_hi:[0,1]
	v_pk_mul_f32 v[18:19], v[32:33], v[18:19] op_sel_hi:[0,1]
	v_pk_mul_f32 v[74:75], v[26:27], v[50:51]
	v_pk_mul_f32 v[76:77], v[18:19], v[52:53]
	global_store_dwordx4 v[2:3], v[74:77], off offset:-2048
	v_mov_b32_e32 v18, v29
	v_mov_b32_e32 v19, v21
	v_mov_b32_e32 v29, v20
	v_pk_mul_f32 v[18:19], v[32:33], v[18:19] op_sel_hi:[0,1]
	v_pk_mul_f32 v[20:21], v[32:33], v[28:29] op_sel_hi:[0,1]
	v_pk_mul_f32 v[80:81], v[18:19], v[56:57]
	v_pk_mul_f32 v[78:79], v[20:21], v[54:55]
	global_store_dwordx4 v[2:3], v[78:81], off offset:-1024
	v_pk_mul_f32 v[18:19], v[32:33], v[22:23] op_sel_hi:[0,1]
	v_pk_mul_f32 v[20:21], v[32:33], v[30:31] op_sel_hi:[0,1]
	v_pk_mul_f32 v[84:85], v[18:19], v[60:61]
	v_pk_mul_f32 v[82:83], v[20:21], v[58:59]
	global_store_dwordx4 v[2:3], v[82:85], off
	v_pk_mul_f32 v[18:19], v[32:33], v[24:25] op_sel_hi:[0,1]
	v_pk_mul_f32 v[20:21], v[32:33], v[34:35] op_sel_hi:[0,1]
	v_pk_mul_f32 v[88:89], v[18:19], v[64:65]
	v_pk_mul_f32 v[86:87], v[20:21], v[62:63]
	global_store_dwordx4 v[2:3], v[86:89], off offset:1024
	v_lshl_add_u64 v[2:3], v[2:3], 0, s[4:5]
	s_cbranch_scc0 .Lfin_loop
